# same hand-out with a fall-back to the original item stride when the grid is not 256 workgroups
# speedup vs baseline: 1.0707x; 1.0027x over previous
; #define TIDX(p) ((p).wv * 64 + (int)__builtin_amdgcn_mbcnt_hi(~0u, __builtin_amdgcn_mbcnt_lo(~0u, 0u)))
; DI void phase0(const PX& p, unsigned char* smem) {
;   float* sm = (float*)smem;
;   if (blockIdx.x == 0 && TIDX(p) < 64) ((unsigned*)(p.ws + OFF_CNT))[TIDX(p)] = 0u;
;   const int n_mod = 384;
;   const int total = n_mod + MIX_TILES + N_FILT_ITEMS;
;   for (int it = blockIdx.x; it < total; it += gridDim.x) {
;     if (it < n_mod) { if (EN & 256) mod_partial(p, it, sm); }
;     else if (it < n_mod + N_FILT_ITEMS) { if (EN & 512) filter_item(p, it - n_mod, sm); }
;     else convert_mixer(p, 0, it - n_mod - N_FILT_ITEMS, sm);
;   }
; }
.LBB0_797:
	s_cmpk_lg_i32 s83, 0x100
	s_cbranch_scc1 .Lp0_orig
	v_readlane_b32 vcc_lo, v255, 63
	s_add_i32 vcc_lo, vcc_lo, 1
	v_writelane_b32 v255, vcc_lo, 63
	v_readlane_b32 vcc_hi, v252, 0
	s_cmp_lt_u32 vcc_lo, 4
	s_cbranch_scc1 .Lp0_early
	s_sub_u32 vcc_lo, vcc_lo, 4
	s_cmp_lt_u32 vcc_hi, 0xa0
	s_cbranch_scc0 .Lp0_light
	s_cmp_ge_u32 vcc_lo, 22
	s_cbranch_scc1 .LBB0_1108
	s_mul_i32 s1, vcc_lo, 0xa0
	s_add_i32 s1, s1, vcc_hi
	s_addk_i32 s1, 0x400
	s_branch .Lp0_chk

; DI void phase0(const PX& p, unsigned char* smem) {
;     ...
;   for (int it = blockIdx.x; it < total; it += gridDim.x) {
;     if (it < n_mod) { if (EN & 256) mod_partial(p, it, sm); }
;     else if (it < n_mod + N_FILT_ITEMS) { if (EN & 512) filter_item(p, it - n_mod, sm); }
;     else convert_mixer(p, 0, it - n_mod - N_FILT_ITEMS, sm);
;   }
.Lp0_early:
	s_lshl_b32 s1, vcc_lo, 8
	s_add_i32 s1, s1, vcc_hi
	s_branch .Lp0_chk
.Lp0_orig:
	s_add_i32 s1, s1, s83
.Lp0_chk:
	s_cmpk_gt_i32 s1, 0x24cf
	s_cbranch_scc1 .LBB0_1108
